# transposed FFN weights stored write-through so the barrier after the GLU phase has little left to write back
# baseline (speedup 1.0000x reference)
.LBB0_803:
	s_lshr_b32 s24, s10, 8
	v_cvt_f32_u32_e32 v37, s24
	s_sub_i32 s33, 0, s24
	s_abs_i32 s26, s27
	s_ashr_i32 s25, s27, 31
	v_rcp_iflag_f32_e32 v37, v37
	s_nop 0
	v_mul_f32_e32 v37, 0x4f7ffffe, v37
	v_cvt_u32_f32_e32 v37, v37
	s_nop 0
	v_readfirstlane_b32 s40, v37
	s_mul_i32 s33, s33, s40
	s_mul_hi_u32 s33, s40, s33
	s_add_i32 s40, s40, s33
	s_mul_hi_u32 s33, s26, s40
	s_mul_i32 s40, s33, s24
	s_sub_i32 s26, s26, s40
	s_add_i32 s41, s33, 1
	s_sub_i32 s40, s26, s24
	s_cmp_ge_u32 s26, s24
	s_cselect_b32 s33, s41, s33
	s_cselect_b32 s26, s40, s26
	s_add_i32 s40, s33, 1
	s_cmp_ge_u32 s26, s24
	s_cselect_b32 s26, s40, s33
	s_xor_b32 s26, s26, s25
	s_sub_i32 s25, s26, s25
	s_mul_i32 s26, s25, s24
	s_lshl_b32 s24, s25, 6
	s_sub_i32 s25, s27, s26
	s_lshl_b32 s26, s25, 8
	s_ashr_i32 s27, s26, 31
	s_lshl_b64 s[40:41], s[26:27], 2
	s_waitcnt lgkmcnt(0)
	s_add_u32 s22, s22, s40
	v_add_u32_e32 v37, s24, v4
	s_addc_u32 s23, s23, s41
	v_lshl_add_u64 v[66:67], s[22:23], 0, v[0:1]
	v_mad_u64_u32 v[38:39], s[22:23], v37, s10, 0
	v_ashrrev_i32_e32 v41, 31, v37
	v_mov_b32_e32 v40, v39
	v_mad_u64_u32 v[40:41], s[22:23], v41, s10, v[40:41]
	v_mov_b32_e32 v39, v40
	v_add_u32_e32 v37, s24, v5
	v_lshl_add_u64 v[46:47], v[38:39], 2, v[66:67]
	v_mad_u64_u32 v[38:39], s[22:23], v37, s10, 0
	v_ashrrev_i32_e32 v41, 31, v37
	v_mov_b32_e32 v40, v39
	v_mad_u64_u32 v[40:41], s[22:23], v41, s10, v[40:41]
	v_mov_b32_e32 v39, v40
	v_add_u32_e32 v37, s24, v6
	v_lshl_add_u64 v[48:49], v[38:39], 2, v[66:67]
	global_load_dwordx4 v[38:41], v[46:47], off nt
	global_load_dwordx4 v[42:45], v[48:49], off nt
	v_mad_u64_u32 v[46:47], s[22:23], v37, s10, 0
	v_ashrrev_i32_e32 v49, 31, v37
	v_mov_b32_e32 v48, v47
	v_mad_u64_u32 v[48:49], s[22:23], v49, s10, v[48:49]
	v_mov_b32_e32 v47, v48
	v_add_u32_e32 v37, s24, v7
	v_lshl_add_u64 v[54:55], v[46:47], 2, v[66:67]
	v_mad_u64_u32 v[46:47], s[22:23], v37, s10, 0
	v_ashrrev_i32_e32 v49, 31, v37
	v_mov_b32_e32 v48, v47
	v_mad_u64_u32 v[48:49], s[22:23], v49, s10, v[48:49]
	v_mov_b32_e32 v47, v48
	v_add_u32_e32 v37, s24, v8
	v_lshl_add_u64 v[56:57], v[46:47], 2, v[66:67]
	global_load_dwordx4 v[46:49], v[54:55], off nt
	global_load_dwordx4 v[50:53], v[56:57], off nt
	v_mad_u64_u32 v[54:55], s[22:23], v37, s10, 0
	v_ashrrev_i32_e32 v57, 31, v37
	v_mov_b32_e32 v56, v55
	v_mad_u64_u32 v[56:57], s[22:23], v57, s10, v[56:57]
	v_mov_b32_e32 v55, v56
	v_add_u32_e32 v37, s24, v9
	v_lshl_add_u64 v[62:63], v[54:55], 2, v[66:67]
	v_mad_u64_u32 v[54:55], s[22:23], v37, s10, 0
	v_ashrrev_i32_e32 v57, 31, v37
	v_mov_b32_e32 v56, v55
	v_mad_u64_u32 v[56:57], s[22:23], v57, s10, v[56:57]
	v_mov_b32_e32 v55, v56
	v_lshl_add_u64 v[64:65], v[54:55], 2, v[66:67]
	global_load_dwordx4 v[54:57], v[62:63], off nt
	global_load_dwordx4 v[58:61], v[64:65], off nt
	v_add_u32_e32 v37, s24, v10
	v_mad_u64_u32 v[62:63], s[22:23], v37, s10, 0
	v_ashrrev_i32_e32 v65, 31, v37
	v_mov_b32_e32 v64, v63
	v_add_u32_e32 v37, s24, v11
	v_mad_u64_u32 v[64:65], s[22:23], v65, s10, v[64:65]
	v_mad_u64_u32 v[68:69], s[22:23], v37, s10, 0
	v_mov_b32_e32 v63, v64
	v_ashrrev_i32_e32 v71, 31, v37
	v_mov_b32_e32 v70, v69
	v_lshl_add_u64 v[62:63], v[62:63], 2, v[66:67]
	v_mad_u64_u32 v[70:71], s[22:23], v71, s10, v[70:71]
	global_load_dwordx4 v[62:65], v[62:63], off nt
	v_mov_b32_e32 v69, v70
	v_lshl_add_u64 v[66:67], v[68:69], 2, v[66:67]
	global_load_dwordx4 v[66:69], v[66:67], off nt
	s_waitcnt vmcnt(0)
	s_barrier
	s_ashr_i32 s25, s24, 31
	s_lshl_b64 s[22:23], s[24:25], 1
	v_add_u32_e32 v37, s26, v12
	s_add_u32 s14, s14, s22
	s_addc_u32 s15, s15, s23
	s_add_i32 s37, s37, s45
	s_cmpk_gt_i32 s37, 0x1ff
	ds_write2_b32 v15, v38, v39 offset1:1
	ds_write2_b32 v15, v40, v41 offset0:2 offset1:3
	ds_write2_b32 v16, v42, v43 offset1:1
	ds_write2_b32 v16, v44, v45 offset0:2 offset1:3
	ds_write2_b32 v17, v46, v47 offset1:1
	ds_write2_b32 v17, v48, v49 offset0:2 offset1:3
	ds_write2_b32 v18, v50, v51 offset1:1
	ds_write2_b32 v18, v52, v53 offset0:2 offset1:3
	ds_write2_b32 v19, v54, v55 offset1:1
	ds_write2_b32 v19, v56, v57 offset0:2 offset1:3
	ds_write2_b32 v20, v58, v59 offset1:1
	ds_write2_b32 v20, v60, v61 offset0:2 offset1:3
	ds_write2_b32 v21, v62, v63 offset1:1
	ds_write2_b32 v21, v64, v65 offset0:2 offset1:3
	ds_write2_b32 v22, v66, v67 offset1:1
	ds_write2_b32 v22, v68, v69 offset0:2 offset1:3
	s_waitcnt lgkmcnt(0)
	s_barrier
	ds_read2_b32 v[38:39], v13 offset1:130
	ds_read2_b32 v[40:41], v14 offset0:65 offset1:195
	ds_read2_b32 v[42:43], v23 offset0:4 offset1:134
	ds_read2_b32 v[44:45], v24 offset0:69 offset1:199
	v_lshl_add_u64 v[46:47], s[14:15], 0, v[2:3]
	s_waitcnt lgkmcnt(2)
	v_cvt_pk_bf16_f32 v38, v38, v40
	v_cvt_pk_bf16_f32 v39, v39, v41
	s_waitcnt lgkmcnt(0)
	v_cvt_pk_bf16_f32 v40, v42, v44
	v_ashrrev_i32_e32 v42, 31, v37
	v_cvt_pk_bf16_f32 v41, v43, v45
	v_mul_lo_u32 v44, s12, v42
	v_mul_lo_u32 v45, s13, v37
	v_mad_u64_u32 v[42:43], s[14:15], s12, v37, 0
	v_add3_u32 v43, v43, v44, v45
	ds_read2_b32 v[44:45], v25 offset0:64 offset1:194
	ds_read2_b32 v[48:49], v26 offset0:1 offset1:131
	ds_read2_b32 v[50:51], v27 offset0:68 offset1:198
	ds_read2_b32 v[52:53], v28 offset0:5 offset1:135
	v_lshl_add_u64 v[42:43], v[42:43], 1, v[46:47]
	global_store_dwordx4 v[42:43], v[38:41], off sc1
	v_add_u32_e32 v42, 64, v37
	v_ashrrev_i32_e32 v43, 31, v42
	s_waitcnt lgkmcnt(2)
	v_cvt_pk_bf16_f32 v38, v44, v48
	v_cvt_pk_bf16_f32 v39, v45, v49
	v_mul_lo_u32 v44, s12, v43
	v_mul_lo_u32 v45, s13, v42
	v_mad_u64_u32 v[42:43], s[14:15], s12, v42, 0
	s_waitcnt lgkmcnt(0)
	v_cvt_pk_bf16_f32 v40, v50, v52
	v_cvt_pk_bf16_f32 v41, v51, v53
	v_add3_u32 v43, v43, v44, v45
	ds_read2_b32 v[44:45], v29 offset1:130
	ds_read2_b32 v[48:49], v30 offset0:65 offset1:195
	ds_read2_b32 v[50:51], v31 offset0:4 offset1:134
	ds_read2_b32 v[52:53], v32 offset0:69 offset1:199
	v_lshl_add_u64 v[42:43], v[42:43], 1, v[46:47]
	global_store_dwordx4 v[42:43], v[38:41], off sc1
	v_add_u32_e32 v42, 0x80, v37
	v_ashrrev_i32_e32 v43, 31, v42
	s_waitcnt lgkmcnt(2)
	v_cvt_pk_bf16_f32 v38, v44, v48
	v_cvt_pk_bf16_f32 v39, v45, v49
	v_mul_lo_u32 v44, s12, v43
	v_mul_lo_u32 v45, s13, v42
	v_mad_u64_u32 v[42:43], s[14:15], s12, v42, 0
	s_waitcnt lgkmcnt(0)
	v_cvt_pk_bf16_f32 v40, v50, v52
	v_cvt_pk_bf16_f32 v41, v51, v53
	v_add3_u32 v43, v43, v44, v45
	ds_read2_b32 v[44:45], v33 offset0:64 offset1:194
	ds_read2_b32 v[48:49], v34 offset0:1 offset1:131
	ds_read2_b32 v[50:51], v35 offset0:68 offset1:198
	ds_read2_b32 v[52:53], v36 offset0:5 offset1:135
	v_lshl_add_u64 v[42:43], v[42:43], 1, v[46:47]
	v_add_u32_e32 v37, 0xc0, v37
	global_store_dwordx4 v[42:43], v[38:41], off sc1
	v_ashrrev_i32_e32 v42, 31, v37
	s_waitcnt lgkmcnt(2)
	v_cvt_pk_bf16_f32 v38, v44, v48
	v_cvt_pk_bf16_f32 v39, v45, v49
	v_mul_lo_u32 v44, s12, v42
	v_mul_lo_u32 v45, s13, v37
	v_mad_u64_u32 v[42:43], s[12:13], s12, v37, 0
	v_add3_u32 v43, v43, v44, v45
	s_waitcnt lgkmcnt(0)
	v_cvt_pk_bf16_f32 v40, v50, v52
	v_cvt_pk_bf16_f32 v41, v51, v53
	v_lshl_add_u64 v[42:43], v[42:43], 1, v[46:47]
	global_store_dwordx4 v[42:43], v[38:41], off sc1
	s_cbranch_scc1 .Lp6_ret
